# same code as the address-reuse version with the retention tile loop and everything after it shifted by 32 bytes (eight never-executed s_nop after an unconditional branch): code-placement check
# baseline (speedup 1.0000x reference)
; #define RT_BAR() do { asm volatile("s_waitcnt lgkmcnt(0)" ::: "memory"); __builtin_amdgcn_s_barrier(); asm volatile("" ::: "memory"); } while (0)
; __device__ __forceinline__ void p2_ret(const Frame& F, ArgsP a, int layer) {
;     ...
;         for (int uu = 0; uu < 2; ++uu) {
;             const int qi = uu ? p : 15 - p, ntile = 2 * (qi + 1);
;             const size_t tokq = (size_t)b * SEQ + qi * 128;
;             f32x16 oacc[4];
; #pragma unroll
;             for (int db = 0; db < 4; ++db)
; #pragma unroll
;                 for (int r = 0; r < 16; ++r) oacc[db][r] = 0.f;
;             asm volatile("s_waitcnt vmcnt(0)" ::: "memory"); RT_BAR();
;             for (int kt = 0; kt < ntile; ++kt) {
.LBB0_355:
	s_xor_b64 s[72:73], s[74:75], -1
	s_and_b64 s[2:3], s[74:75], exec
	s_waitcnt vmcnt(0)
	s_cselect_b32 s96, s89, s50
	s_waitcnt lgkmcnt(0)
	s_barrier
	s_lshl_b32 s19, s96, 7
	s_lshl_b32 s11, s96, 8
	v_mov_b32_e32 v34, 0
	s_lshl_b32 s29, s96, 1
	s_add_i32 s97, s81, s19
	s_bitset1_b32 s11, 7
	s_mov_b32 s31, 0
	s_mov_b32 s27, s88
	s_mov_b32 s30, 0
	s_mov_b32 s91, 0
	v_mov_b32_e32 v35, v34
	v_mov_b32_e32 v36, v34
	v_mov_b32_e32 v37, v34
	v_mov_b32_e32 v38, v34
	v_mov_b32_e32 v39, v34
	v_mov_b32_e32 v40, v34
	v_mov_b32_e32 v41, v34
	v_mov_b32_e32 v42, v34
	v_mov_b32_e32 v43, v34
	v_mov_b32_e32 v44, v34
	v_mov_b32_e32 v45, v34
	v_mov_b32_e32 v46, v34
	v_mov_b32_e32 v47, v34
	v_mov_b32_e32 v48, v34
	v_mov_b32_e32 v49, v34
	v_mov_b32_e32 v50, v34
	v_mov_b32_e32 v51, v34
	v_mov_b32_e32 v52, v34
	v_mov_b32_e32 v53, v34
	v_mov_b32_e32 v54, v34
	v_mov_b32_e32 v55, v34
	v_mov_b32_e32 v56, v34
	v_mov_b32_e32 v57, v34
	v_mov_b32_e32 v58, v34
	v_mov_b32_e32 v59, v34
	v_mov_b32_e32 v60, v34
	v_mov_b32_e32 v61, v34
	v_mov_b32_e32 v62, v34
	v_mov_b32_e32 v63, v34
	v_mov_b32_e32 v64, v34
	v_mov_b32_e32 v65, v34
	v_mov_b32_e32 v66, v34
	v_mov_b32_e32 v67, v34
	v_mov_b32_e32 v68, v34
	v_mov_b32_e32 v69, v34
	v_mov_b32_e32 v70, v34
	v_mov_b32_e32 v71, v34
	v_mov_b32_e32 v72, v34
	v_mov_b32_e32 v73, v34
	v_mov_b32_e32 v74, v34
	v_mov_b32_e32 v75, v34
	v_mov_b32_e32 v76, v34
	v_mov_b32_e32 v77, v34
	v_mov_b32_e32 v78, v34
	v_mov_b32_e32 v79, v34
	v_mov_b32_e32 v80, v34
	v_mov_b32_e32 v81, v34
	v_mov_b32_e32 v82, v34
	v_mov_b32_e32 v83, v34
	v_mov_b32_e32 v84, v34
	v_mov_b32_e32 v85, v34
	v_mov_b32_e32 v86, v34
	v_mov_b32_e32 v87, v34
	v_mov_b32_e32 v88, v34
	v_mov_b32_e32 v89, v34
	v_mov_b32_e32 v90, v34
	v_mov_b32_e32 v91, v34
	v_mov_b32_e32 v92, v34
	v_mov_b32_e32 v93, v34
	v_mov_b32_e32 v94, v34
	v_mov_b32_e32 v95, v34
	v_mov_b32_e32 v96, v34
	v_mov_b32_e32 v97, v34
	s_branch .LBB0_358
	s_nop 0
	s_nop 0
	s_nop 0
	s_nop 0
	s_nop 0
	s_nop 0
	s_nop 0
	s_nop 0
